# gate epi<1>: second half-tile's running-sum stash loads issued with the first half's (idle VGPRs, SADDR form), one exposed round trip instead of two
# speedup vs baseline: 1.0002x; 1.0002x over previous
.LBB0_1016:
	v_mov_b32_e32 v160, v0
	v_readlane_b32 s10, v248, 39
	v_ashrrev_i32_e32 v161, 31, v160
	v_lshl_add_u64 v[162:163], v[160:161], 4, s[14:15]
	v_lshl_add_u32 v161, v160, 4, s10
	s_cmp_gt_u32 s68, 1
	s_mov_b64 s[10:11], -1
	s_cbranch_scc0 .LBB0_1022
	s_and_b32 s10, s68, -2
	s_cmp_lg_u32 s10, 6
	s_mov_b64 s[10:11], -1
	s_cbranch_scc0 .LBB0_1019
	global_load_dwordx4 v[212:215], v[162:163], off
	v_add_co_u32_e32 v176, vcc, 0x2000, v162
	v_cvt_f32_ubyte1_e32 v217, v180
	s_nop 0
	v_addc_co_u32_e32 v177, vcc, 0, v163, vcc
	global_load_dwordx4 v[154:157], v[176:177], off
	v_add_co_u32_e32 v174, vcc, 0x4000, v162
	v_cvt_f32_ubyte0_e32 v216, v180
	s_nop 0
	v_addc_co_u32_e32 v175, vcc, 0, v163, vcc
	global_load_dwordx4 v[150:153], v[174:175], off
	v_add_co_u32_e32 v172, vcc, 0x6000, v162
	s_mov_b32 s10, 0x10000
	s_nop 0
	v_addc_co_u32_e32 v173, vcc, 0, v163, vcc
	global_load_dwordx4 v[146:149], v[172:173], off
	v_add_co_u32_e32 v170, vcc, 0x8000, v162
	s_nop 1
	v_addc_co_u32_e32 v171, vcc, 0, v163, vcc
	global_load_dwordx4 v[142:145], v[170:171], off
	v_add_co_u32_e32 v168, vcc, 0xa000, v162
	s_nop 1
	v_addc_co_u32_e32 v169, vcc, 0, v163, vcc
	global_load_dwordx4 v[138:141], v[168:169], off
	v_add_co_u32_e32 v166, vcc, 0xc000, v162
	s_nop 1
	v_addc_co_u32_e32 v167, vcc, 0, v163, vcc
	global_load_dwordx4 v[134:137], v[166:167], off
	v_add_co_u32_e32 v164, vcc, 0xe000, v162
	s_nop 1
	v_addc_co_u32_e32 v165, vcc, 0, v163, vcc
	global_load_dwordx4 v[130:133], v[164:165], off
	v_lshlrev_b32_e32 v224, 4, v160
	v_add_u32_e32 v225, 0x10000, v224
	global_load_dwordx4 v[236:239], v225, s[14:15]
	v_add_u32_e32 v254, 0x12000, v224
	global_load_dwordx4 v[240:243], v254, s[14:15]
	v_add_u32_e32 v225, 0x14000, v224
	global_load_dwordx4 v[244:247], v225, s[14:15]
	v_add_u32_e32 v254, 0x16000, v224
	global_load_dwordx4 v[250:253], v254, s[14:15]
	s_waitcnt vmcnt(4)
	v_lshlrev_b32_e32 v218, 16, v212
	v_and_b32_e32 v219, 0xffff0000, v212
	v_pk_fma_f32 v[216:217], v[216:217], v[126:127], v[218:219]
	v_lshlrev_b32_e32 v218, 16, v213
	v_cvt_pk_bf16_f32 v212, v216, v217
	v_cvt_f32_ubyte3_e32 v217, v180
	v_cvt_f32_ubyte2_e32 v216, v180
	v_and_b32_e32 v219, 0xffff0000, v213
	v_pk_fma_f32 v[216:217], v[216:217], v[128:129], v[218:219]
	v_lshlrev_b32_e32 v218, 16, v214
	v_cvt_pk_bf16_f32 v213, v216, v217
	v_cvt_f32_ubyte1_e32 v217, v181
	v_cvt_f32_ubyte0_e32 v216, v181
	v_and_b32_e32 v219, 0xffff0000, v214
	v_pk_fma_f32 v[216:217], v[216:217], v[122:123], v[218:219]
	v_lshlrev_b32_e32 v218, 16, v215
	v_cvt_pk_bf16_f32 v214, v216, v217
	v_cvt_f32_ubyte3_e32 v217, v181
	v_cvt_f32_ubyte2_e32 v216, v181
	v_and_b32_e32 v219, 0xffff0000, v215
	v_pk_fma_f32 v[216:217], v[216:217], v[124:125], v[218:219]
	v_cvt_f32_ubyte1_e32 v219, v196
	v_cvt_pk_bf16_f32 v215, v216, v217
	global_store_dwordx4 v[162:163], v[212:215], off
	v_cvt_f32_ubyte0_e32 v218, v196
	s_nop 0
	v_cvt_f32_ubyte1_e32 v213, v182
	v_cvt_f32_ubyte0_e32 v212, v182
	v_lshlrev_b32_e32 v214, 16, v154
	v_and_b32_e32 v215, 0xffff0000, v154
	v_pk_fma_f32 v[212:213], v[212:213], v[118:119], v[214:215]
	v_lshlrev_b32_e32 v214, 16, v155
	v_cvt_pk_bf16_f32 v154, v212, v213
	v_cvt_f32_ubyte3_e32 v213, v182
	v_cvt_f32_ubyte2_e32 v212, v182
	v_and_b32_e32 v215, 0xffff0000, v155
	v_pk_fma_f32 v[212:213], v[212:213], v[120:121], v[214:215]
	v_lshlrev_b32_e32 v214, 16, v156
	v_cvt_pk_bf16_f32 v155, v212, v213
	v_cvt_f32_ubyte1_e32 v213, v183
	v_cvt_f32_ubyte0_e32 v212, v183
	v_and_b32_e32 v215, 0xffff0000, v156
	v_pk_fma_f32 v[212:213], v[212:213], v[110:111], v[214:215]
	v_lshlrev_b32_e32 v214, 16, v157
	v_cvt_pk_bf16_f32 v156, v212, v213
	v_cvt_f32_ubyte3_e32 v213, v183
	v_cvt_f32_ubyte2_e32 v212, v183
	v_and_b32_e32 v215, 0xffff0000, v157
	v_pk_fma_f32 v[212:213], v[212:213], v[112:113], v[214:215]
	s_nop 0
	v_cvt_pk_bf16_f32 v157, v212, v213
	global_store_dwordx4 v[176:177], v[154:157], off
	v_add_co_u32_e32 v176, vcc, s10, v162
	s_nop 0
	v_cvt_f32_ubyte1_e32 v155, v184
	v_cvt_f32_ubyte0_e32 v154, v184
	v_lshlrev_b32_e32 v156, 16, v150
	v_and_b32_e32 v157, 0xffff0000, v150
	v_pk_fma_f32 v[154:155], v[154:155], v[114:115], v[156:157]
	v_lshlrev_b32_e32 v156, 16, v151
	v_cvt_pk_bf16_f32 v150, v154, v155
	v_cvt_f32_ubyte3_e32 v155, v184
	v_cvt_f32_ubyte2_e32 v154, v184
	v_and_b32_e32 v157, 0xffff0000, v151
	v_pk_fma_f32 v[154:155], v[154:155], v[116:117], v[156:157]
	v_lshlrev_b32_e32 v156, 16, v152
	v_cvt_pk_bf16_f32 v151, v154, v155
	v_cvt_f32_ubyte1_e32 v155, v185
	v_cvt_f32_ubyte0_e32 v154, v185
	v_and_b32_e32 v157, 0xffff0000, v152
	v_pk_fma_f32 v[154:155], v[154:155], v[106:107], v[156:157]
	v_lshlrev_b32_e32 v156, 16, v153
	v_cvt_pk_bf16_f32 v152, v154, v155
	v_cvt_f32_ubyte3_e32 v155, v185
	v_cvt_f32_ubyte2_e32 v154, v185
	v_and_b32_e32 v157, 0xffff0000, v153
	v_pk_fma_f32 v[154:155], v[154:155], v[108:109], v[156:157]
	v_addc_co_u32_e32 v177, vcc, 0, v163, vcc
	v_cvt_pk_bf16_f32 v153, v154, v155
	global_store_dwordx4 v[174:175], v[150:153], off
	s_mov_b32 s10, 0x12000
	v_add_co_u32_e32 v212, vcc, s10, v162
	v_cvt_f32_ubyte1_e32 v151, v186
	v_cvt_f32_ubyte0_e32 v150, v186
	v_lshlrev_b32_e32 v152, 16, v146
	v_and_b32_e32 v153, 0xffff0000, v146
	v_pk_fma_f32 v[150:151], v[150:151], v[102:103], v[152:153]
	v_lshlrev_b32_e32 v152, 16, v147
	v_cvt_pk_bf16_f32 v146, v150, v151
	v_cvt_f32_ubyte3_e32 v151, v186
	v_cvt_f32_ubyte2_e32 v150, v186
	v_and_b32_e32 v153, 0xffff0000, v147
	v_pk_fma_f32 v[150:151], v[150:151], v[104:105], v[152:153]
	v_lshlrev_b32_e32 v152, 16, v148
	v_cvt_pk_bf16_f32 v147, v150, v151
	v_cvt_f32_ubyte1_e32 v151, v187
	v_cvt_f32_ubyte0_e32 v150, v187
	v_and_b32_e32 v153, 0xffff0000, v148
	v_pk_fma_f32 v[150:151], v[150:151], v[94:95], v[152:153]
	v_lshlrev_b32_e32 v152, 16, v149
	v_cvt_pk_bf16_f32 v148, v150, v151
	v_cvt_f32_ubyte3_e32 v151, v187
	v_cvt_f32_ubyte2_e32 v150, v187
	v_and_b32_e32 v153, 0xffff0000, v149
	v_pk_fma_f32 v[150:151], v[150:151], v[96:97], v[152:153]
	v_addc_co_u32_e32 v213, vcc, 0, v163, vcc
	v_cvt_pk_bf16_f32 v149, v150, v151
	global_store_dwordx4 v[172:173], v[146:149], off
	s_mov_b32 s10, 0x14000
	v_add_co_u32_e32 v214, vcc, s10, v162
	v_cvt_f32_ubyte1_e32 v147, v188
	v_cvt_f32_ubyte0_e32 v146, v188
	v_lshlrev_b32_e32 v148, 16, v142
	v_and_b32_e32 v149, 0xffff0000, v142
	v_pk_fma_f32 v[146:147], v[146:147], v[98:99], v[148:149]
	v_lshlrev_b32_e32 v148, 16, v143
	v_cvt_pk_bf16_f32 v142, v146, v147
	v_cvt_f32_ubyte3_e32 v147, v188
	v_cvt_f32_ubyte2_e32 v146, v188
	v_and_b32_e32 v149, 0xffff0000, v143
	v_pk_fma_f32 v[146:147], v[146:147], v[100:101], v[148:149]
	v_lshlrev_b32_e32 v148, 16, v144
	v_cvt_pk_bf16_f32 v143, v146, v147
	v_cvt_f32_ubyte1_e32 v147, v189
	v_cvt_f32_ubyte0_e32 v146, v189
	v_and_b32_e32 v149, 0xffff0000, v144
	v_pk_fma_f32 v[146:147], v[146:147], v[90:91], v[148:149]
	v_lshlrev_b32_e32 v148, 16, v145
	v_cvt_pk_bf16_f32 v144, v146, v147
	v_cvt_f32_ubyte3_e32 v147, v189
	v_cvt_f32_ubyte2_e32 v146, v189
	v_and_b32_e32 v149, 0xffff0000, v145
	v_pk_fma_f32 v[146:147], v[146:147], v[92:93], v[148:149]
	v_addc_co_u32_e32 v215, vcc, 0, v163, vcc
	v_cvt_pk_bf16_f32 v145, v146, v147
	global_store_dwordx4 v[170:171], v[142:145], off
	v_add_u32_e32 v225, 0x18000, v224
	s_nop 0
	global_load_dwordx4 v[146:149], v225, s[14:15]
	s_mov_b32 s10, 0x16000
	v_add_co_u32_e32 v216, vcc, s10, v162
	v_cvt_f32_ubyte1_e32 v143, v190
	v_cvt_f32_ubyte0_e32 v142, v190
	v_lshlrev_b32_e32 v144, 16, v138
	v_and_b32_e32 v145, 0xffff0000, v138
	v_pk_fma_f32 v[142:143], v[142:143], v[86:87], v[144:145]
	v_lshlrev_b32_e32 v144, 16, v139
	v_cvt_pk_bf16_f32 v138, v142, v143
	v_cvt_f32_ubyte3_e32 v143, v190
	v_cvt_f32_ubyte2_e32 v142, v190
	v_and_b32_e32 v145, 0xffff0000, v139
	v_pk_fma_f32 v[142:143], v[142:143], v[88:89], v[144:145]
	v_lshlrev_b32_e32 v144, 16, v140
	v_cvt_pk_bf16_f32 v139, v142, v143
	v_cvt_f32_ubyte1_e32 v143, v191
	v_cvt_f32_ubyte0_e32 v142, v191
	v_and_b32_e32 v145, 0xffff0000, v140
	v_pk_fma_f32 v[142:143], v[142:143], v[78:79], v[144:145]
	v_lshlrev_b32_e32 v144, 16, v141
	v_cvt_pk_bf16_f32 v140, v142, v143
	v_cvt_f32_ubyte3_e32 v143, v191
	v_cvt_f32_ubyte2_e32 v142, v191
	v_and_b32_e32 v145, 0xffff0000, v141
	v_pk_fma_f32 v[142:143], v[142:143], v[80:81], v[144:145]
	v_addc_co_u32_e32 v217, vcc, 0, v163, vcc
	v_cvt_pk_bf16_f32 v141, v142, v143
	global_store_dwordx4 v[168:169], v[138:141], off
	v_add_u32_e32 v254, 0x1a000, v224
	s_nop 0
	global_load_dwordx4 v[142:145], v254, s[14:15]
	s_mov_b32 s10, 0x18000
	v_add_co_u32_e32 v152, vcc, s10, v162
	v_cvt_f32_ubyte1_e32 v139, v192
	v_cvt_f32_ubyte0_e32 v138, v192
	v_lshlrev_b32_e32 v140, 16, v134
	v_and_b32_e32 v141, 0xffff0000, v134
	v_pk_fma_f32 v[138:139], v[138:139], v[82:83], v[140:141]
	v_lshlrev_b32_e32 v140, 16, v135
	v_cvt_pk_bf16_f32 v134, v138, v139
	v_cvt_f32_ubyte3_e32 v139, v192
	v_cvt_f32_ubyte2_e32 v138, v192
	v_and_b32_e32 v141, 0xffff0000, v135
	v_pk_fma_f32 v[138:139], v[138:139], v[84:85], v[140:141]
	v_lshlrev_b32_e32 v140, 16, v136
	v_cvt_pk_bf16_f32 v135, v138, v139
	v_cvt_f32_ubyte1_e32 v139, v193
	v_cvt_f32_ubyte0_e32 v138, v193
	v_and_b32_e32 v141, 0xffff0000, v136
	v_pk_fma_f32 v[138:139], v[138:139], v[74:75], v[140:141]
	v_lshlrev_b32_e32 v140, 16, v137
	v_cvt_pk_bf16_f32 v136, v138, v139
	v_cvt_f32_ubyte3_e32 v139, v193
	v_cvt_f32_ubyte2_e32 v138, v193
	v_and_b32_e32 v141, 0xffff0000, v137
	v_pk_fma_f32 v[138:139], v[138:139], v[76:77], v[140:141]
	v_addc_co_u32_e32 v153, vcc, 0, v163, vcc
	v_cvt_pk_bf16_f32 v137, v138, v139
	global_store_dwordx4 v[166:167], v[134:137], off
	s_mov_b32 s10, 0x1a000
	v_add_co_u32_e32 v150, vcc, s10, v162
	v_cvt_f32_ubyte1_e32 v135, v194
	v_cvt_f32_ubyte0_e32 v134, v194
	v_lshlrev_b32_e32 v136, 16, v130
	v_and_b32_e32 v137, 0xffff0000, v130
	v_pk_fma_f32 v[134:135], v[134:135], v[70:71], v[136:137]
	v_lshlrev_b32_e32 v136, 16, v131
	v_cvt_pk_bf16_f32 v130, v134, v135
	v_cvt_f32_ubyte3_e32 v135, v194
	v_cvt_f32_ubyte2_e32 v134, v194
	v_and_b32_e32 v137, 0xffff0000, v131
	v_pk_fma_f32 v[134:135], v[134:135], v[72:73], v[136:137]
	v_lshlrev_b32_e32 v136, 16, v132
	v_cvt_pk_bf16_f32 v131, v134, v135
	v_cvt_f32_ubyte1_e32 v135, v195
	v_cvt_f32_ubyte0_e32 v134, v195
	v_and_b32_e32 v137, 0xffff0000, v132
	v_pk_fma_f32 v[134:135], v[134:135], v[66:67], v[136:137]
	v_lshlrev_b32_e32 v136, 16, v133
	v_cvt_pk_bf16_f32 v132, v134, v135
	v_cvt_f32_ubyte3_e32 v135, v195
	v_cvt_f32_ubyte2_e32 v134, v195
	v_and_b32_e32 v137, 0xffff0000, v133
	v_pk_fma_f32 v[134:135], v[134:135], v[68:69], v[136:137]
	v_addc_co_u32_e32 v151, vcc, 0, v163, vcc
	v_cvt_pk_bf16_f32 v133, v134, v135
	global_store_dwordx4 v[164:165], v[130:133], off
	v_lshl_add_u32 v134, v160, 4, 0
	v_add_u32_e32 v222, 0x20f80, v134
	ds_read_b128 v[130:133], v161
	ds_read_b128 v[138:141], v222
	v_add_u32_e32 v223, 0x22f80, v134
	ds_read_b128 v[134:137], v223
	s_mov_b64 s[10:11], 0
	s_waitcnt vmcnt(10)
	v_lshlrev_b32_e32 v220, 16, v236
	v_and_b32_e32 v221, 0xffff0000, v236
	v_pk_fma_f32 v[218:219], v[218:219], v[62:63], v[220:221]
	v_lshlrev_b32_e32 v220, 16, v237
	v_cvt_pk_bf16_f32 v154, v218, v219
	v_cvt_f32_ubyte3_e32 v219, v196
	v_cvt_f32_ubyte2_e32 v218, v196
	v_and_b32_e32 v221, 0xffff0000, v237
	v_pk_fma_f32 v[218:219], v[218:219], v[64:65], v[220:221]
	v_lshlrev_b32_e32 v220, 16, v238
	v_cvt_pk_bf16_f32 v155, v218, v219
	v_cvt_f32_ubyte1_e32 v219, v197
	v_cvt_f32_ubyte0_e32 v218, v197
	v_and_b32_e32 v221, 0xffff0000, v238
	v_pk_fma_f32 v[218:219], v[218:219], v[58:59], v[220:221]
	v_lshlrev_b32_e32 v220, 16, v239
	v_cvt_pk_bf16_f32 v156, v218, v219
	v_cvt_f32_ubyte3_e32 v219, v197
	v_cvt_f32_ubyte2_e32 v218, v197
	v_and_b32_e32 v221, 0xffff0000, v239
	v_pk_fma_f32 v[218:219], v[218:219], v[60:61], v[220:221]
	s_nop 0
	v_cvt_pk_bf16_f32 v157, v218, v219
	global_store_dwordx4 v[176:177], v[154:157], off
	s_nop 1
	v_cvt_f32_ubyte1_e32 v155, v198
	v_cvt_f32_ubyte0_e32 v154, v198
	v_lshlrev_b32_e32 v156, 16, v240
	v_and_b32_e32 v157, 0xffff0000, v240
	v_pk_fma_f32 v[154:155], v[154:155], v[54:55], v[156:157]
	v_cvt_f32_ubyte3_e32 v157, v198
	v_cvt_f32_ubyte2_e32 v156, v198
	v_lshlrev_b32_e32 v164, 16, v241
	v_and_b32_e32 v165, 0xffff0000, v241
	v_pk_fma_f32 v[156:157], v[156:157], v[56:57], v[164:165]
	v_cvt_pk_bf16_f32 v154, v154, v155
	v_cvt_pk_bf16_f32 v155, v156, v157
	v_cvt_f32_ubyte1_e32 v157, v199
	v_cvt_f32_ubyte0_e32 v156, v199
	v_lshlrev_b32_e32 v164, 16, v242
	v_and_b32_e32 v165, 0xffff0000, v242
	v_pk_fma_f32 v[156:157], v[156:157], v[46:47], v[164:165]
	v_cvt_f32_ubyte3_e32 v165, v199
	v_cvt_f32_ubyte2_e32 v164, v199
	v_lshlrev_b32_e32 v166, 16, v243
	v_and_b32_e32 v167, 0xffff0000, v243
	v_pk_fma_f32 v[164:165], v[164:165], v[48:49], v[166:167]
	v_cvt_pk_bf16_f32 v156, v156, v157
	v_cvt_pk_bf16_f32 v157, v164, v165
	global_store_dwordx4 v[212:213], v[154:157], off
	v_lshlrev_b32_e32 v164, 16, v245
	v_and_b32_e32 v165, 0xffff0000, v245
	v_cvt_f32_ubyte1_e32 v155, v200
	v_cvt_f32_ubyte0_e32 v154, v200
	v_lshlrev_b32_e32 v156, 16, v244
	v_and_b32_e32 v157, 0xffff0000, v244
	v_pk_fma_f32 v[154:155], v[154:155], v[50:51], v[156:157]
	v_cvt_f32_ubyte3_e32 v157, v200
	v_cvt_f32_ubyte2_e32 v156, v200
	v_pk_fma_f32 v[156:157], v[156:157], v[52:53], v[164:165]
	v_cvt_pk_bf16_f32 v154, v154, v155
	v_cvt_pk_bf16_f32 v155, v156, v157
	v_cvt_f32_ubyte1_e32 v157, v201
	v_cvt_f32_ubyte0_e32 v156, v201
	v_lshlrev_b32_e32 v164, 16, v246
	v_and_b32_e32 v165, 0xffff0000, v246
	v_pk_fma_f32 v[156:157], v[156:157], v[42:43], v[164:165]
	v_cvt_f32_ubyte3_e32 v165, v201
	v_cvt_f32_ubyte2_e32 v164, v201
	v_lshlrev_b32_e32 v166, 16, v247
	v_and_b32_e32 v167, 0xffff0000, v247
	v_pk_fma_f32 v[164:165], v[164:165], v[44:45], v[166:167]
	v_cvt_pk_bf16_f32 v156, v156, v157
	v_cvt_pk_bf16_f32 v157, v164, v165
	global_store_dwordx4 v[214:215], v[154:157], off
	v_lshlrev_b32_e32 v164, 16, v251
	v_and_b32_e32 v165, 0xffff0000, v251
	v_cvt_f32_ubyte1_e32 v155, v205
	v_cvt_f32_ubyte0_e32 v154, v205
	v_lshlrev_b32_e32 v156, 16, v250
	v_and_b32_e32 v157, 0xffff0000, v250
	v_pk_fma_f32 v[154:155], v[154:155], v[38:39], v[156:157]
	v_cvt_f32_ubyte3_e32 v157, v205
	v_cvt_f32_ubyte2_e32 v156, v205
	v_pk_fma_f32 v[156:157], v[156:157], v[40:41], v[164:165]
	v_cvt_pk_bf16_f32 v154, v154, v155
	v_cvt_pk_bf16_f32 v155, v156, v157
	v_cvt_f32_ubyte1_e32 v157, v207
	v_cvt_f32_ubyte0_e32 v156, v207
	v_lshlrev_b32_e32 v164, 16, v252
	v_and_b32_e32 v165, 0xffff0000, v252
	v_pk_fma_f32 v[156:157], v[156:157], v[30:31], v[164:165]
	v_cvt_f32_ubyte3_e32 v165, v207
	v_cvt_f32_ubyte2_e32 v164, v207
	v_lshlrev_b32_e32 v166, 16, v253
	v_and_b32_e32 v167, 0xffff0000, v253
	v_pk_fma_f32 v[164:165], v[164:165], v[32:33], v[166:167]
	v_cvt_pk_bf16_f32 v156, v156, v157
	v_cvt_pk_bf16_f32 v157, v164, v165
	global_store_dwordx4 v[216:217], v[154:157], off
	s_nop 1
	v_cvt_f32_ubyte1_e32 v155, v208
	v_cvt_f32_ubyte0_e32 v154, v208
	s_waitcnt vmcnt(8)
	v_lshlrev_b32_e32 v156, 16, v146
	v_and_b32_e32 v157, 0xffff0000, v146
	v_pk_fma_f32 v[154:155], v[154:155], v[34:35], v[156:157]
	v_lshlrev_b32_e32 v156, 16, v147
	v_cvt_pk_bf16_f32 v146, v154, v155
	v_cvt_f32_ubyte3_e32 v155, v208
	v_cvt_f32_ubyte2_e32 v154, v208
	v_and_b32_e32 v157, 0xffff0000, v147
	v_pk_fma_f32 v[154:155], v[154:155], v[36:37], v[156:157]
	v_lshlrev_b32_e32 v156, 16, v148
	v_cvt_pk_bf16_f32 v147, v154, v155
	v_cvt_f32_ubyte1_e32 v155, v209
	v_cvt_f32_ubyte0_e32 v154, v209
	v_and_b32_e32 v157, 0xffff0000, v148
	v_pk_fma_f32 v[154:155], v[154:155], v[26:27], v[156:157]
	v_lshlrev_b32_e32 v156, 16, v149
	v_cvt_pk_bf16_f32 v148, v154, v155
	v_cvt_f32_ubyte3_e32 v155, v209
	v_cvt_f32_ubyte2_e32 v154, v209
	v_and_b32_e32 v157, 0xffff0000, v149
	v_pk_fma_f32 v[154:155], v[154:155], v[28:29], v[156:157]
	s_nop 0
	v_cvt_pk_bf16_f32 v149, v154, v155
	global_store_dwordx4 v[152:153], v[146:149], off
	s_nop 1
	v_cvt_f32_ubyte1_e32 v147, v210
	v_cvt_f32_ubyte0_e32 v146, v210
	s_waitcnt vmcnt(7)
	v_lshlrev_b32_e32 v148, 16, v142
	v_and_b32_e32 v149, 0xffff0000, v142
	v_pk_fma_f32 v[146:147], v[146:147], v[22:23], v[148:149]
	v_lshlrev_b32_e32 v148, 16, v143
	v_cvt_pk_bf16_f32 v142, v146, v147
	v_cvt_f32_ubyte3_e32 v147, v210
	v_cvt_f32_ubyte2_e32 v146, v210
	v_and_b32_e32 v149, 0xffff0000, v143
	v_pk_fma_f32 v[146:147], v[146:147], v[24:25], v[148:149]
	v_lshlrev_b32_e32 v148, 16, v144
	v_cvt_pk_bf16_f32 v143, v146, v147
	v_cvt_f32_ubyte1_e32 v147, v211
	v_cvt_f32_ubyte0_e32 v146, v211
	v_and_b32_e32 v149, 0xffff0000, v144
	v_pk_fma_f32 v[146:147], v[146:147], v[14:15], v[148:149]
	v_lshlrev_b32_e32 v148, 16, v145
	v_cvt_pk_bf16_f32 v144, v146, v147
	v_cvt_f32_ubyte3_e32 v147, v211
	v_cvt_f32_ubyte2_e32 v146, v211
	v_and_b32_e32 v149, 0xffff0000, v145
	v_pk_fma_f32 v[146:147], v[146:147], v[16:17], v[148:149]
	s_nop 0
	v_cvt_pk_bf16_f32 v145, v146, v147
	global_store_dwordx4 v[150:151], v[142:145], off
	s_waitcnt lgkmcnt(2)
	s_nop 0
	v_cvt_f32_ubyte1_e32 v143, v130
	v_cvt_f32_ubyte0_e32 v142, v130
	s_waitcnt lgkmcnt(1)
	v_lshlrev_b32_e32 v144, 16, v138
	v_and_b32_e32 v145, 0xffff0000, v138
	v_pk_fma_f32 v[142:143], v[142:143], v[18:19], v[144:145]
	v_lshlrev_b32_e32 v144, 16, v139
	v_cvt_pk_bf16_f32 v138, v142, v143
	v_cvt_f32_ubyte3_e32 v143, v130
	v_cvt_f32_ubyte2_e32 v142, v130
	v_and_b32_e32 v145, 0xffff0000, v139
	v_pk_fma_f32 v[142:143], v[142:143], v[20:21], v[144:145]
	v_lshlrev_b32_e32 v144, 16, v140
	v_cvt_pk_bf16_f32 v139, v142, v143
	v_cvt_f32_ubyte1_e32 v143, v131
	v_cvt_f32_ubyte0_e32 v142, v131
	v_and_b32_e32 v145, 0xffff0000, v140
	v_pk_fma_f32 v[142:143], v[142:143], v[10:11], v[144:145]
	v_lshlrev_b32_e32 v130, 16, v141
	v_cvt_pk_bf16_f32 v140, v142, v143
	v_cvt_f32_ubyte3_e32 v143, v131
	v_cvt_f32_ubyte2_e32 v142, v131
	v_and_b32_e32 v131, 0xffff0000, v141
	v_pk_fma_f32 v[130:131], v[142:143], v[12:13], v[130:131]
	s_nop 0
	v_cvt_pk_bf16_f32 v141, v130, v131
	ds_write_b128 v222, v[138:141]
	v_cvt_f32_ubyte1_e32 v131, v132
	v_cvt_f32_ubyte0_e32 v130, v132
	s_waitcnt lgkmcnt(1)
	v_lshlrev_b32_e32 v138, 16, v134
	v_and_b32_e32 v139, 0xffff0000, v134
	v_pk_fma_f32 v[130:131], v[130:131], v[6:7], v[138:139]
	v_cvt_f32_ubyte3_e32 v139, v132
	v_cvt_f32_ubyte2_e32 v138, v132
	v_lshlrev_b32_e32 v134, 16, v135
	v_and_b32_e32 v135, 0xffff0000, v135
	v_pk_fma_f32 v[134:135], v[138:139], v[8:9], v[134:135]
	v_cvt_pk_bf16_f32 v130, v130, v131
	v_cvt_pk_bf16_f32 v131, v134, v135
	v_cvt_f32_ubyte1_e32 v135, v133
	v_cvt_f32_ubyte0_e32 v134, v133
	v_lshlrev_b32_e32 v138, 16, v136
	v_and_b32_e32 v139, 0xffff0000, v136
	v_pk_fma_f32 v[134:135], v[134:135], v[2:3], v[138:139]
	v_lshlrev_b32_e32 v136, 16, v137
	v_cvt_pk_bf16_f32 v132, v134, v135
	v_cvt_f32_ubyte3_e32 v135, v133
	v_cvt_f32_ubyte2_e32 v134, v133
	v_and_b32_e32 v137, 0xffff0000, v137
	v_pk_fma_f32 v[134:135], v[134:135], v[4:5], v[136:137]
	s_nop 0
	v_cvt_pk_bf16_f32 v133, v134, v135
	ds_write_b128 v223, v[130:133]
.LBB0_1019:
	s_andn2_b64 vcc, exec, s[10:11]
	s_cbranch_vccnz .LBB0_1021
	s_lshl_b32 s10, s67, 8
	global_load_dwordx4 v[168:171], v[162:163], off
	s_add_i32 s10, s10, s62
	v_and_or_b32 v166, v160, 15, s10
	s_lshl_b32 s10, s70, 8
	v_lshrrev_b32_e32 v130, 1, v160
	v_and_or_b32 v130, v130, 24, s10
	s_movk_i32 s10, 0x2000
	v_or_b32_e32 v164, s63, v130
	v_add_co_u32_e32 v130, vcc, s10, v162
	s_movk_i32 s10, 0x4000
	s_nop 0
	v_addc_co_u32_e32 v131, vcc, 0, v163, vcc
	global_load_dwordx4 v[154:157], v[130:131], off
	v_add_co_u32_e32 v130, vcc, s10, v162
	s_movk_i32 s10, 0x6000
	s_nop 0
	v_addc_co_u32_e32 v131, vcc, 0, v163, vcc
	global_load_dwordx4 v[150:153], v[130:131], off
	v_add_co_u32_e32 v130, vcc, s10, v162
	s_mov_b32 s10, 0x8000
	s_nop 0
	v_addc_co_u32_e32 v131, vcc, 0, v163, vcc
	global_load_dwordx4 v[146:149], v[130:131], off
	v_add_co_u32_e32 v130, vcc, s10, v162
	s_mov_b32 s10, 0xa000
	s_nop 0
	v_addc_co_u32_e32 v131, vcc, 0, v163, vcc
	global_load_dwordx4 v[142:145], v[130:131], off
	v_add_co_u32_e32 v130, vcc, s10, v162
	s_mov_b32 s10, 0xc000
	s_nop 0
	v_addc_co_u32_e32 v131, vcc, 0, v163, vcc
	global_load_dwordx4 v[138:141], v[130:131], off
	v_add_co_u32_e32 v130, vcc, s10, v162
	s_mov_b32 s10, 0xe000
	s_nop 0
	v_addc_co_u32_e32 v131, vcc, 0, v163, vcc
	global_load_dwordx4 v[134:137], v[130:131], off
	v_add_co_u32_e32 v130, vcc, s10, v162
	v_cvt_f32_ubyte1_e32 v177, v180
	s_nop 0
	v_addc_co_u32_e32 v131, vcc, 0, v163, vcc
	global_load_dwordx4 v[130:133], v[130:131], off
	v_cvt_f32_ubyte0_e32 v176, v180
	v_ashrrev_i32_e32 v167, 31, v166
	v_cvt_f32_ubyte1_e32 v213, v181
	v_cvt_f32_ubyte0_e32 v212, v181
	v_ashrrev_i32_e32 v165, 31, v164
	v_lshlrev_b64 v[174:175], 12, v[166:167]
	v_lshl_add_u64 v[174:175], s[8:9], 0, v[174:175]
	s_mov_b32 s10, 0x10000
	v_lshlrev_b32_e32 v224, 4, v160
	v_add_u32_e32 v225, 0x10000, v224
	global_load_dwordx4 v[216:219], v225, s[14:15]
	v_add_u32_e32 v254, 0x12000, v224
	global_load_dwordx4 v[220:223], v254, s[14:15]
	v_add_u32_e32 v225, 0x14000, v224
	global_load_dwordx4 v[236:239], v225, s[14:15]
	v_add_u32_e32 v254, 0x16000, v224
	global_load_dwordx4 v[240:243], v254, s[14:15]
	v_add_u32_e32 v225, 0x18000, v224
	global_load_dwordx4 v[244:247], v225, s[14:15]
	v_add_u32_e32 v254, 0x1a000, v224
	global_load_dwordx4 v[250:253], v254, s[14:15]
	s_waitcnt vmcnt(6)
	v_lshlrev_b32_e32 v172, 16, v168
	v_and_b32_e32 v173, 0xffff0000, v168
	v_pk_fma_f32 v[172:173], v[176:177], v[126:127], v[172:173]
	v_lshlrev_b32_e32 v168, 16, v169
	v_and_b32_e32 v169, 0xffff0000, v169
	v_cvt_f32_ubyte3_e32 v177, v180
	v_cvt_f32_ubyte2_e32 v176, v180
	v_pk_fma_f32 v[168:169], v[176:177], v[128:129], v[168:169]
	v_lshlrev_b32_e32 v176, 16, v170
	v_and_b32_e32 v177, 0xffff0000, v170
	v_pk_fma_f32 v[176:177], v[212:213], v[122:123], v[176:177]
	v_lshlrev_b32_e32 v170, 16, v171
	v_and_b32_e32 v171, 0xffff0000, v171
	v_cvt_f32_ubyte3_e32 v213, v181
	v_cvt_f32_ubyte2_e32 v212, v181
	v_pk_fma_f32 v[212:213], v[212:213], v[124:125], v[170:171]
	v_cvt_pk_bf16_f32 v171, v168, v169
	v_lshlrev_b64 v[168:169], 1, v[164:165]
	v_cvt_pk_bf16_f32 v170, v172, v173
	v_cvt_pk_bf16_f32 v172, v176, v177
	v_cvt_pk_bf16_f32 v173, v212, v213
	v_lshl_add_u64 v[164:165], v[174:175], 0, v[168:169]
	global_store_dwordx4 v[164:165], v[170:173], off
	v_cvt_f32_ubyte1_e32 v175, v183
	v_cvt_f32_ubyte0_e32 v174, v183
	v_lshlrev_b32_e32 v170, 16, v154
	v_and_b32_e32 v171, 0xffff0000, v154
	v_cvt_f32_ubyte1_e32 v173, v182
	v_cvt_f32_ubyte0_e32 v172, v182
	v_pk_fma_f32 v[170:171], v[172:173], v[118:119], v[170:171]
	v_lshlrev_b32_e32 v154, 16, v155
	v_and_b32_e32 v155, 0xffff0000, v155
	v_cvt_f32_ubyte3_e32 v173, v182
	v_cvt_f32_ubyte2_e32 v172, v182
	v_pk_fma_f32 v[172:173], v[172:173], v[120:121], v[154:155]
	v_lshlrev_b32_e32 v154, 16, v156
	v_and_b32_e32 v155, 0xffff0000, v156
	v_pk_fma_f32 v[174:175], v[174:175], v[110:111], v[154:155]
	v_lshlrev_b32_e32 v154, 16, v157
	v_and_b32_e32 v155, 0xffff0000, v157
	v_cvt_f32_ubyte3_e32 v157, v183
	v_cvt_f32_ubyte2_e32 v156, v183
	v_pk_fma_f32 v[176:177], v[156:157], v[112:113], v[154:155]
	v_cvt_pk_bf16_f32 v154, v170, v171
	v_cvt_pk_bf16_f32 v155, v172, v173
	v_cvt_pk_bf16_f32 v156, v174, v175
	v_cvt_pk_bf16_f32 v157, v176, v177
	global_store_dwordx4 v[164:165], v[154:157], off offset:256
	v_cvt_f32_ubyte1_e32 v171, v184
	v_cvt_f32_ubyte0_e32 v170, v184
	v_lshlrev_b32_e32 v156, 16, v150
	v_and_b32_e32 v157, 0xffff0000, v150
	v_or_b32_e32 v154, 16, v166
	v_pk_fma_f32 v[156:157], v[170:171], v[114:115], v[156:157]
	v_lshlrev_b32_e32 v150, 16, v151
	v_and_b32_e32 v151, 0xffff0000, v151
	v_cvt_f32_ubyte3_e32 v171, v184
	v_cvt_f32_ubyte2_e32 v170, v184
	v_ashrrev_i32_e32 v155, 31, v154
	v_pk_fma_f32 v[170:171], v[170:171], v[116:117], v[150:151]
	v_lshlrev_b32_e32 v150, 16, v152
	v_and_b32_e32 v151, 0xffff0000, v152
	v_cvt_f32_ubyte1_e32 v173, v185
	v_cvt_f32_ubyte0_e32 v172, v185
	v_lshlrev_b64 v[154:155], 12, v[154:155]
	v_pk_fma_f32 v[172:173], v[172:173], v[106:107], v[150:151]
	v_lshlrev_b32_e32 v150, 16, v153
	v_and_b32_e32 v151, 0xffff0000, v153
	v_cvt_f32_ubyte3_e32 v153, v185
	v_cvt_f32_ubyte2_e32 v152, v185
	v_pk_fma_f32 v[174:175], v[152:153], v[108:109], v[150:151]
	v_lshl_add_u64 v[154:155], s[8:9], 0, v[154:155]
	v_cvt_pk_bf16_f32 v150, v156, v157
	v_cvt_pk_bf16_f32 v151, v170, v171
	v_cvt_pk_bf16_f32 v152, v172, v173
	v_cvt_pk_bf16_f32 v153, v174, v175
	v_lshl_add_u64 v[154:155], v[154:155], 0, v[168:169]
	global_store_dwordx4 v[154:155], v[150:153], off
	v_cvt_f32_ubyte1_e32 v157, v187
	v_cvt_f32_ubyte0_e32 v156, v187
	v_lshlrev_b32_e32 v150, 16, v146
	v_and_b32_e32 v151, 0xffff0000, v146
	v_cvt_f32_ubyte1_e32 v153, v186
	v_cvt_f32_ubyte0_e32 v152, v186
	v_pk_fma_f32 v[150:151], v[152:153], v[102:103], v[150:151]
	v_lshlrev_b32_e32 v146, 16, v147
	v_and_b32_e32 v147, 0xffff0000, v147
	v_cvt_f32_ubyte3_e32 v153, v186
	v_cvt_f32_ubyte2_e32 v152, v186
	v_pk_fma_f32 v[152:153], v[152:153], v[104:105], v[146:147]
	v_lshlrev_b32_e32 v146, 16, v148
	v_and_b32_e32 v147, 0xffff0000, v148
	v_pk_fma_f32 v[156:157], v[156:157], v[94:95], v[146:147]
	v_lshlrev_b32_e32 v146, 16, v149
	v_and_b32_e32 v147, 0xffff0000, v149
	v_cvt_f32_ubyte3_e32 v149, v187
	v_cvt_f32_ubyte2_e32 v148, v187
	v_pk_fma_f32 v[170:171], v[148:149], v[96:97], v[146:147]
	v_cvt_pk_bf16_f32 v146, v150, v151
	v_cvt_pk_bf16_f32 v147, v152, v153
	v_cvt_pk_bf16_f32 v148, v156, v157
	v_cvt_pk_bf16_f32 v149, v170, v171
	global_store_dwordx4 v[154:155], v[146:149], off offset:256
	v_cvt_f32_ubyte1_e32 v151, v188
	v_cvt_f32_ubyte0_e32 v150, v188
	v_lshlrev_b32_e32 v148, 16, v142
	v_and_b32_e32 v149, 0xffff0000, v142
	v_or_b32_e32 v146, 32, v166
	v_pk_fma_f32 v[148:149], v[150:151], v[98:99], v[148:149]
	v_lshlrev_b32_e32 v142, 16, v143
	v_and_b32_e32 v143, 0xffff0000, v143
	v_cvt_f32_ubyte3_e32 v151, v188
	v_cvt_f32_ubyte2_e32 v150, v188
	v_ashrrev_i32_e32 v147, 31, v146
	v_pk_fma_f32 v[150:151], v[150:151], v[100:101], v[142:143]
	v_lshlrev_b32_e32 v142, 16, v144
	v_and_b32_e32 v143, 0xffff0000, v144
	v_cvt_f32_ubyte1_e32 v153, v189
	v_cvt_f32_ubyte0_e32 v152, v189
	v_lshlrev_b64 v[146:147], 12, v[146:147]
	v_pk_fma_f32 v[152:153], v[152:153], v[90:91], v[142:143]
	v_lshlrev_b32_e32 v142, 16, v145
	v_and_b32_e32 v143, 0xffff0000, v145
	v_cvt_f32_ubyte3_e32 v145, v189
	v_cvt_f32_ubyte2_e32 v144, v189
	v_pk_fma_f32 v[154:155], v[144:145], v[92:93], v[142:143]
	v_lshl_add_u64 v[146:147], s[8:9], 0, v[146:147]
	v_cvt_pk_bf16_f32 v142, v148, v149
	v_cvt_pk_bf16_f32 v143, v150, v151
	v_cvt_pk_bf16_f32 v144, v152, v153
	v_cvt_pk_bf16_f32 v145, v154, v155
	v_lshl_add_u64 v[146:147], v[146:147], 0, v[168:169]
	global_store_dwordx4 v[146:147], v[142:145], off
	v_cvt_f32_ubyte1_e32 v149, v191
	v_cvt_f32_ubyte0_e32 v148, v191
	v_lshlrev_b32_e32 v142, 16, v138
	v_and_b32_e32 v143, 0xffff0000, v138
	v_cvt_f32_ubyte1_e32 v145, v190
	v_cvt_f32_ubyte0_e32 v144, v190
	v_pk_fma_f32 v[142:143], v[144:145], v[86:87], v[142:143]
	v_lshlrev_b32_e32 v138, 16, v139
	v_and_b32_e32 v139, 0xffff0000, v139
	v_cvt_f32_ubyte3_e32 v145, v190
	v_cvt_f32_ubyte2_e32 v144, v190
	v_pk_fma_f32 v[144:145], v[144:145], v[88:89], v[138:139]
	v_lshlrev_b32_e32 v138, 16, v140
	v_and_b32_e32 v139, 0xffff0000, v140
	v_pk_fma_f32 v[148:149], v[148:149], v[78:79], v[138:139]
	v_lshlrev_b32_e32 v138, 16, v141
	v_and_b32_e32 v139, 0xffff0000, v141
	v_cvt_f32_ubyte3_e32 v141, v191
	v_cvt_f32_ubyte2_e32 v140, v191
	v_pk_fma_f32 v[150:151], v[140:141], v[80:81], v[138:139]
	v_cvt_pk_bf16_f32 v138, v142, v143
	v_cvt_pk_bf16_f32 v139, v144, v145
	v_cvt_pk_bf16_f32 v140, v148, v149
	v_cvt_pk_bf16_f32 v141, v150, v151
	global_store_dwordx4 v[146:147], v[138:141], off offset:256
	v_cvt_f32_ubyte1_e32 v143, v192
	v_cvt_f32_ubyte0_e32 v142, v192
	v_lshlrev_b32_e32 v140, 16, v134
	v_and_b32_e32 v141, 0xffff0000, v134
	v_or_b32_e32 v138, 48, v166
	v_pk_fma_f32 v[140:141], v[142:143], v[82:83], v[140:141]
	v_lshlrev_b32_e32 v134, 16, v135
	v_and_b32_e32 v135, 0xffff0000, v135
	v_cvt_f32_ubyte3_e32 v143, v192
	v_cvt_f32_ubyte2_e32 v142, v192
	v_ashrrev_i32_e32 v139, 31, v138
	v_pk_fma_f32 v[142:143], v[142:143], v[84:85], v[134:135]
	v_lshlrev_b32_e32 v134, 16, v136
	v_and_b32_e32 v135, 0xffff0000, v136
	v_cvt_f32_ubyte1_e32 v145, v193
	v_cvt_f32_ubyte0_e32 v144, v193
	v_lshlrev_b64 v[138:139], 12, v[138:139]
	v_pk_fma_f32 v[144:145], v[144:145], v[74:75], v[134:135]
	v_lshlrev_b32_e32 v134, 16, v137
	v_and_b32_e32 v135, 0xffff0000, v137
	v_cvt_f32_ubyte3_e32 v137, v193
	v_cvt_f32_ubyte2_e32 v136, v193
	v_pk_fma_f32 v[146:147], v[136:137], v[76:77], v[134:135]
	v_lshl_add_u64 v[138:139], s[8:9], 0, v[138:139]
	v_cvt_pk_bf16_f32 v134, v140, v141
	v_cvt_pk_bf16_f32 v135, v142, v143
	v_cvt_pk_bf16_f32 v136, v144, v145
	v_cvt_pk_bf16_f32 v137, v146, v147
	v_lshl_add_u64 v[138:139], v[138:139], 0, v[168:169]
	global_store_dwordx4 v[138:139], v[134:137], off
	v_cvt_f32_ubyte1_e32 v141, v195
	v_cvt_f32_ubyte0_e32 v140, v195
	v_lshlrev_b32_e32 v134, 16, v130
	v_and_b32_e32 v135, 0xffff0000, v130
	v_cvt_f32_ubyte1_e32 v137, v194
	v_cvt_f32_ubyte0_e32 v136, v194
	v_pk_fma_f32 v[134:135], v[136:137], v[70:71], v[134:135]
	v_lshlrev_b32_e32 v130, 16, v131
	v_and_b32_e32 v131, 0xffff0000, v131
	v_cvt_f32_ubyte3_e32 v137, v194
	v_cvt_f32_ubyte2_e32 v136, v194
	v_pk_fma_f32 v[136:137], v[136:137], v[72:73], v[130:131]
	v_lshlrev_b32_e32 v130, 16, v132
	v_and_b32_e32 v131, 0xffff0000, v132
	v_pk_fma_f32 v[140:141], v[140:141], v[66:67], v[130:131]
	v_lshlrev_b32_e32 v130, 16, v133
	v_and_b32_e32 v131, 0xffff0000, v133
	v_cvt_f32_ubyte3_e32 v133, v195
	v_cvt_f32_ubyte2_e32 v132, v195
	v_pk_fma_f32 v[142:143], v[132:133], v[68:69], v[130:131]
	v_cvt_pk_bf16_f32 v130, v134, v135
	v_cvt_pk_bf16_f32 v131, v136, v137
	v_cvt_pk_bf16_f32 v132, v140, v141
	v_cvt_pk_bf16_f32 v133, v142, v143
	global_store_dwordx4 v[138:139], v[130:133], off offset:256
	v_add_co_u32_e32 v134, vcc, s10, v162
	s_mov_b32 s10, 0x12000
	s_nop 0
	v_addc_co_u32_e32 v135, vcc, 0, v163, vcc
	v_add_co_u32_e32 v134, vcc, s10, v162
	s_mov_b32 s10, 0x14000
	s_nop 0
	v_addc_co_u32_e32 v135, vcc, 0, v163, vcc
	v_add_co_u32_e32 v134, vcc, s10, v162
	s_mov_b32 s10, 0x16000
	s_nop 0
	v_addc_co_u32_e32 v135, vcc, 0, v163, vcc
	v_add_co_u32_e32 v134, vcc, s10, v162
	s_mov_b32 s10, 0x18000
	s_nop 0
	v_addc_co_u32_e32 v135, vcc, 0, v163, vcc
	v_add_co_u32_e32 v134, vcc, s10, v162
	s_mov_b32 s10, 0x1a000
	s_nop 0
	v_addc_co_u32_e32 v135, vcc, 0, v163, vcc
	v_add_co_u32_e32 v134, vcc, s10, v162
	v_cvt_f32_ubyte1_e32 v177, v196
	s_nop 0
	v_addc_co_u32_e32 v135, vcc, 0, v163, vcc
	v_cvt_f32_ubyte0_e32 v176, v196
	v_cvt_f32_ubyte1_e32 v213, v197
	v_cvt_f32_ubyte0_e32 v212, v197
	s_mov_b64 s[10:11], 0x80000
	v_lshl_add_u32 v134, v160, 4, 0
	v_add_u32_e32 v135, 0x20f80, v134
	ds_read_b128 v[130:133], v161
	ds_read_b128 v[138:141], v135
	v_add_u32_e32 v134, 0x22f80, v134
	ds_read_b128 v[134:137], v134
	s_waitcnt vmcnt(8)
	v_lshlrev_b32_e32 v174, 16, v216
	v_and_b32_e32 v175, 0xffff0000, v216
	v_pk_fma_f32 v[174:175], v[176:177], v[62:63], v[174:175]
	v_lshlrev_b32_e32 v150, 16, v217
	v_and_b32_e32 v151, 0xffff0000, v217
	v_cvt_f32_ubyte3_e32 v177, v196
	v_cvt_f32_ubyte2_e32 v176, v196
	v_pk_fma_f32 v[176:177], v[176:177], v[64:65], v[150:151]
	v_lshlrev_b32_e32 v150, 16, v218
	v_and_b32_e32 v151, 0xffff0000, v218
	v_pk_fma_f32 v[212:213], v[212:213], v[58:59], v[150:151]
	v_lshlrev_b32_e32 v150, 16, v219
	v_and_b32_e32 v151, 0xffff0000, v219
	v_cvt_f32_ubyte3_e32 v153, v197
	v_cvt_f32_ubyte2_e32 v152, v197
	v_pk_fma_f32 v[214:215], v[152:153], v[60:61], v[150:151]
	v_cvt_pk_bf16_f32 v150, v174, v175
	v_lshl_add_u64 v[174:175], v[164:165], 0, s[10:11]
	s_mov_b32 s10, 0x80000
	v_cvt_pk_bf16_f32 v151, v176, v177
	v_add_co_u32_e32 v176, vcc, s10, v164
	v_cvt_pk_bf16_f32 v152, v212, v213
	v_cvt_pk_bf16_f32 v153, v214, v215
	v_addc_co_u32_e32 v177, vcc, 0, v165, vcc
	global_store_dwordx4 v[176:177], v[150:153], off
	v_cvt_f32_ubyte1_e32 v177, v199
	v_cvt_f32_ubyte0_e32 v176, v199
	v_lshlrev_b32_e32 v150, 16, v220
	v_and_b32_e32 v151, 0xffff0000, v220
	v_cvt_f32_ubyte1_e32 v153, v198
	v_cvt_f32_ubyte0_e32 v152, v198
	v_pk_fma_f32 v[150:151], v[152:153], v[54:55], v[150:151]
	v_lshlrev_b32_e32 v152, 16, v221
	v_and_b32_e32 v153, 0xffff0000, v221
	v_cvt_f32_ubyte3_e32 v155, v198
	v_cvt_f32_ubyte2_e32 v154, v198
	v_pk_fma_f32 v[152:153], v[154:155], v[56:57], v[152:153]
	v_lshlrev_b32_e32 v154, 16, v222
	v_and_b32_e32 v155, 0xffff0000, v222
	v_pk_fma_f32 v[154:155], v[176:177], v[46:47], v[154:155]
	v_lshlrev_b32_e32 v156, 16, v223
	v_and_b32_e32 v157, 0xffff0000, v223
	v_cvt_f32_ubyte3_e32 v177, v199
	v_cvt_f32_ubyte2_e32 v176, v199
	v_pk_fma_f32 v[156:157], v[176:177], v[48:49], v[156:157]
	v_cvt_pk_bf16_f32 v150, v150, v151
	v_cvt_pk_bf16_f32 v151, v152, v153
	v_cvt_pk_bf16_f32 v152, v154, v155
	v_cvt_pk_bf16_f32 v153, v156, v157
	global_store_dwordx4 v[174:175], v[150:153], off offset:256
	v_cvt_f32_ubyte3_e32 v155, v200
	v_cvt_f32_ubyte2_e32 v154, v200
	v_lshlrev_b32_e32 v150, 16, v236
	v_and_b32_e32 v151, 0xffff0000, v236
	v_cvt_f32_ubyte1_e32 v153, v200
	v_cvt_f32_ubyte0_e32 v152, v200
	v_pk_fma_f32 v[150:151], v[152:153], v[50:51], v[150:151]
	v_lshlrev_b32_e32 v152, 16, v237
	v_and_b32_e32 v153, 0xffff0000, v237
	v_pk_fma_f32 v[152:153], v[154:155], v[52:53], v[152:153]
	v_lshlrev_b32_e32 v154, 16, v238
	v_and_b32_e32 v155, 0xffff0000, v238
	v_cvt_f32_ubyte1_e32 v157, v201
	v_cvt_f32_ubyte0_e32 v156, v201
	v_pk_fma_f32 v[154:155], v[156:157], v[42:43], v[154:155]
	v_lshlrev_b32_e32 v156, 16, v239
	v_and_b32_e32 v157, 0xffff0000, v239
	v_cvt_f32_ubyte3_e32 v167, v201
	v_cvt_f32_ubyte2_e32 v166, v201
	s_mov_b64 s[10:11], 0x90000
	v_pk_fma_f32 v[156:157], v[166:167], v[44:45], v[156:157]
	v_cvt_pk_bf16_f32 v150, v150, v151
	v_cvt_pk_bf16_f32 v151, v152, v153
	v_cvt_pk_bf16_f32 v152, v154, v155
	v_lshl_add_u64 v[154:155], v[164:165], 0, s[10:11]
	s_mov_b32 s10, 0x90000
	v_cvt_pk_bf16_f32 v153, v156, v157
	v_add_co_u32_e32 v156, vcc, s10, v164
	v_cvt_f32_ubyte1_e32 v167, v207
	s_nop 0
	v_addc_co_u32_e32 v157, vcc, 0, v165, vcc
	global_store_dwordx4 v[156:157], v[150:153], off
	v_cvt_f32_ubyte3_e32 v157, v205
	v_cvt_f32_ubyte2_e32 v156, v205
	v_lshlrev_b32_e32 v150, 16, v240
	v_and_b32_e32 v151, 0xffff0000, v240
	v_cvt_f32_ubyte1_e32 v153, v205
	v_cvt_f32_ubyte0_e32 v152, v205
	v_pk_fma_f32 v[150:151], v[152:153], v[38:39], v[150:151]
	v_lshlrev_b32_e32 v152, 16, v241
	v_and_b32_e32 v153, 0xffff0000, v241
	v_pk_fma_f32 v[152:153], v[156:157], v[40:41], v[152:153]
	v_lshlrev_b32_e32 v156, 16, v242
	v_and_b32_e32 v157, 0xffff0000, v242
	v_cvt_f32_ubyte0_e32 v166, v207
	v_pk_fma_f32 v[156:157], v[166:167], v[30:31], v[156:157]
	v_lshlrev_b32_e32 v166, 16, v243
	v_and_b32_e32 v167, 0xffff0000, v243
	v_cvt_f32_ubyte3_e32 v169, v207
	v_cvt_f32_ubyte2_e32 v168, v207
	v_pk_fma_f32 v[166:167], v[168:169], v[32:33], v[166:167]
	v_cvt_pk_bf16_f32 v150, v150, v151
	v_cvt_pk_bf16_f32 v151, v152, v153
	v_cvt_pk_bf16_f32 v152, v156, v157
	v_cvt_pk_bf16_f32 v153, v166, v167
	global_store_dwordx4 v[154:155], v[150:153], off offset:256
	v_cvt_f32_ubyte1_e32 v155, v209
	v_cvt_f32_ubyte0_e32 v154, v209
	v_lshlrev_b32_e32 v150, 16, v244
	v_and_b32_e32 v151, 0xffff0000, v244
	v_cvt_f32_ubyte1_e32 v153, v208
	v_cvt_f32_ubyte0_e32 v152, v208
	v_pk_fma_f32 v[150:151], v[152:153], v[34:35], v[150:151]
	v_lshlrev_b32_e32 v146, 16, v245
	v_and_b32_e32 v147, 0xffff0000, v245
	v_cvt_f32_ubyte3_e32 v153, v208
	v_cvt_f32_ubyte2_e32 v152, v208
	v_pk_fma_f32 v[152:153], v[152:153], v[36:37], v[146:147]
	v_lshlrev_b32_e32 v146, 16, v246
	v_and_b32_e32 v147, 0xffff0000, v246
	v_pk_fma_f32 v[154:155], v[154:155], v[26:27], v[146:147]
	v_lshlrev_b32_e32 v146, 16, v247
	v_and_b32_e32 v147, 0xffff0000, v247
	v_cvt_f32_ubyte3_e32 v149, v209
	v_cvt_f32_ubyte2_e32 v148, v209
	s_mov_b64 s[10:11], 0xa0000
	v_pk_fma_f32 v[156:157], v[148:149], v[28:29], v[146:147]
	v_cvt_pk_bf16_f32 v146, v150, v151
	v_lshl_add_u64 v[150:151], v[164:165], 0, s[10:11]
	s_mov_b32 s10, 0xa0000
	v_cvt_pk_bf16_f32 v147, v152, v153
	v_add_co_u32_e32 v152, vcc, s10, v164
	v_cvt_pk_bf16_f32 v148, v154, v155
	v_cvt_pk_bf16_f32 v149, v156, v157
	v_addc_co_u32_e32 v153, vcc, 0, v165, vcc
	global_store_dwordx4 v[152:153], v[146:149], off
	v_cvt_f32_ubyte1_e32 v153, v211
	v_cvt_f32_ubyte0_e32 v152, v211
	v_lshlrev_b32_e32 v146, 16, v250
	v_and_b32_e32 v147, 0xffff0000, v250
	v_cvt_f32_ubyte1_e32 v149, v210
	v_cvt_f32_ubyte0_e32 v148, v210
	v_pk_fma_f32 v[146:147], v[148:149], v[22:23], v[146:147]
	v_lshlrev_b32_e32 v142, 16, v251
	v_and_b32_e32 v143, 0xffff0000, v251
	v_cvt_f32_ubyte3_e32 v149, v210
	v_cvt_f32_ubyte2_e32 v148, v210
	v_pk_fma_f32 v[148:149], v[148:149], v[24:25], v[142:143]
	v_lshlrev_b32_e32 v142, 16, v252
	v_and_b32_e32 v143, 0xffff0000, v252
	v_pk_fma_f32 v[152:153], v[152:153], v[14:15], v[142:143]
	v_lshlrev_b32_e32 v142, 16, v253
	v_and_b32_e32 v143, 0xffff0000, v253
	v_cvt_f32_ubyte3_e32 v145, v211
	v_cvt_f32_ubyte2_e32 v144, v211
	v_pk_fma_f32 v[154:155], v[144:145], v[16:17], v[142:143]
	v_cvt_pk_bf16_f32 v142, v146, v147
	v_cvt_pk_bf16_f32 v143, v148, v149
	v_cvt_pk_bf16_f32 v144, v152, v153
	v_cvt_pk_bf16_f32 v145, v154, v155
	global_store_dwordx4 v[150:151], v[142:145], off offset:256
	s_waitcnt lgkmcnt(2)
	v_cvt_f32_ubyte1_e32 v147, v131
	v_cvt_f32_ubyte0_e32 v146, v131
	s_waitcnt lgkmcnt(1)
	v_lshlrev_b32_e32 v142, 16, v138
	v_and_b32_e32 v143, 0xffff0000, v138
	v_cvt_f32_ubyte1_e32 v145, v130
	v_cvt_f32_ubyte0_e32 v144, v130
	v_pk_fma_f32 v[142:143], v[144:145], v[18:19], v[142:143]
	v_lshlrev_b32_e32 v138, 16, v139
	v_and_b32_e32 v139, 0xffff0000, v139
	v_cvt_f32_ubyte3_e32 v145, v130
	v_cvt_f32_ubyte2_e32 v144, v130
	v_pk_fma_f32 v[144:145], v[144:145], v[20:21], v[138:139]
	v_lshlrev_b32_e32 v138, 16, v140
	v_and_b32_e32 v139, 0xffff0000, v140
	v_pk_fma_f32 v[146:147], v[146:147], v[10:11], v[138:139]
	v_lshlrev_b32_e32 v138, 16, v141
	v_and_b32_e32 v139, 0xffff0000, v141
	v_cvt_f32_ubyte3_e32 v141, v131
	v_cvt_f32_ubyte2_e32 v140, v131
	s_mov_b64 s[10:11], 0xb0000
	v_pk_fma_f32 v[130:131], v[140:141], v[12:13], v[138:139]
	v_cvt_pk_bf16_f32 v138, v142, v143
	v_lshl_add_u64 v[142:143], v[164:165], 0, s[10:11]
	s_mov_b32 s10, 0xb0000
	v_cvt_pk_bf16_f32 v141, v130, v131
	v_add_co_u32_e32 v130, vcc, s10, v164
	v_cvt_pk_bf16_f32 v139, v144, v145
	v_cvt_pk_bf16_f32 v140, v146, v147
	v_addc_co_u32_e32 v131, vcc, 0, v165, vcc
	global_store_dwordx4 v[130:131], v[138:141], off
	s_waitcnt lgkmcnt(0)
	v_lshlrev_b32_e32 v130, 16, v134
	v_and_b32_e32 v131, 0xffff0000, v134
	v_cvt_f32_ubyte1_e32 v139, v132
	v_cvt_f32_ubyte0_e32 v138, v132
	v_pk_fma_f32 v[130:131], v[138:139], v[6:7], v[130:131]
	v_lshlrev_b32_e32 v134, 16, v135
	v_and_b32_e32 v135, 0xffff0000, v135
	v_cvt_f32_ubyte3_e32 v139, v132
	v_cvt_f32_ubyte2_e32 v138, v132
	v_pk_fma_f32 v[134:135], v[138:139], v[8:9], v[134:135]
	v_lshlrev_b32_e32 v138, 16, v136
	v_and_b32_e32 v139, 0xffff0000, v136
	v_cvt_f32_ubyte1_e32 v141, v133
	v_cvt_f32_ubyte0_e32 v140, v133
	v_pk_fma_f32 v[138:139], v[140:141], v[2:3], v[138:139]
	v_lshlrev_b32_e32 v136, 16, v137
	v_and_b32_e32 v137, 0xffff0000, v137
	v_cvt_f32_ubyte3_e32 v141, v133
	v_cvt_f32_ubyte2_e32 v140, v133
	v_pk_fma_f32 v[136:137], v[140:141], v[4:5], v[136:137]
	v_cvt_pk_bf16_f32 v130, v130, v131
	v_cvt_pk_bf16_f32 v131, v134, v135
	v_cvt_pk_bf16_f32 v132, v138, v139
	v_cvt_pk_bf16_f32 v133, v136, v137
	global_store_dwordx4 v[142:143], v[130:133], off offset:256
